# pass 2: end-of-stage LDS wait leaves the stage's last (wave-private) mask-word write in flight across the barrier
# speedup vs baseline: 1.0132x; 1.0045x over previous
.Lp2_skip4:
	ds_write_b32 v162, v33
	v_add_u32_e32 v162, 8, v162
	s_waitcnt lgkmcnt(1)
	s_barrier
	s_add_u32 s18, s18, 1
	s_cmp_ge_u32 s18, s13
	s_cbranch_scc1 .Lp2_drain1

.Lp2_skip16:
	ds_write_b32 v162, v33
	v_add_u32_e32 v162, 8, v162
	s_waitcnt lgkmcnt(1)
	s_barrier
	s_add_u32 s0, s0, 0xffffff00
	s_addc_u32 s1, s1, -1
	s_add_u32 s18, s18, 1
	s_cmp_ge_u32 s18, s13
	s_cbranch_scc1 .Lp2_drain0
	s_branch .Lp2_c1
